# attention K LDS swizzle made conflict-free for ds_read_b128 (4-bit XOR key)
# speedup vs baseline: 1.0023x; 1.0023x over previous
; __device__ __forceinline__ int v_st(int k, int c) { const int kk = (k & ~0xC) | ((k & 4) << 1) | ((k & 8) >> 1); return ((kk >> 3) * 4 + (c >> 5)) * 512 + ((kk & 7) * 32 + (c & 31)) * 2; }
; __device__ __forceinline__ int v_rd_base(int lane) { return ((lane & 3) << 3) | (((lane >> 2) & 3) << 6) | (((lane >> 4) & 1) << 5) | (((lane >> 5) & 1) << 8); }
; #define SWRITE(b, i) do { *(bf16x8*)((char*)V_lds + (b) * SHM_V + vst0) = sr_[i].vs0;          \
;     *(bf16x8*)((char*)V_lds + (b) * SHM_V + vst1) = sr_[i].vs1; int kc = sc * 2;               \
;     *(bf16x8*)((char*)K_lds + (b) * SHM_K + KSWZ(sr, kc)) = sr_[i].ks0;                       \
;     *(bf16x8*)((char*)K_lds + (b) * SHM_K + KSWZ(32 + sr, kc)) = sr_[i].ks1; } while (0)
; __device__ __forceinline__ void attn_body(const bf16_t* __restrict__ Qb, const bf16_t* __restrict__ Kh, const bf16_t* __restrict__ Vh,
;                                           bf16_t* __restrict__ Ob, const bf16_t* __restrict__ AGb, int seq, char* lds) {
;     ...
;   const bf16_t* Qw = Qb + (long)(wid * QBLK + r32) * LDQ + hi * 8;
; #pragma unroll
;   for (int d0 = 0; d0 < 8; ++d0) qr[d0] = *reinterpret_cast<const bf16x8*>(Qw + d0 * 16);
;   const int sr = tid >> 4, sc = (tid & 15) * 8, vst0 = v_st(sr, sc), vst1 = v_st(32 + sr, sc);
;   const int vb0 = (int)(uintptr_t)V_lds + v_rd_base(lane);
;   const unsigned goff0 = (unsigned)(sr * LDK + sc) * 2u, goff1 = (unsigned)((32 + sr) * LDK + sc) * 2u;
;   struct { bf16x8 vs0, vs1, ks0, ks1; } sr_[2];
;     ...
;   f32x16 pA0, pA1, pB0, pB1; float mnA, mnB, alA, alB; bf16x8 pa0, pa1, pa2, pa3; const int NT = seq / KVBLK;
;   constexpr int SE = 0, SO = 1;
;   SLOAD(SE, 0); asm volatile("s_waitcnt vmcnt(0)" ::: "memory"); SWRITE(0, SE); __syncthreads();
;   qkt(pA0, pA1, K_lds, qr, r32, hi); partialSM(pA0, pA1, m_reg, mnA, alA);
.LBB0_198:
	s_lshr_b32 s23, s3, 2
	s_mul_i32 s1, s18, 0x8800
	s_mul_hi_i32 s0, s18, 0x8800
	s_add_u32 s26, s8, s1
	s_addc_u32 s27, s9, s0
	s_lshl_b32 s28, s3, 7
	s_lshl_b32 s0, s3, 8
	s_add_u32 s20, s26, s0
	s_addc_u32 s21, s27, 0
	s_mul_hi_u32 s22, s23, 0x210000
	s_mul_i32 s23, s23, 0x210000
	v_mov_b32_e32 v64, v190
	s_add_u32 s4, s12, s23
	s_addc_u32 s5, s13, s22
	v_ashrrev_i32_e32 v18, 4, v64
	v_lshlrev_b32_e32 v19, 3, v64
	v_and_b32_e32 v0, 0x78, v19
	v_add_u32_e32 v21, 32, v18
	s_add_u32 s0, s10, s23
	v_lshlrev_b32_e32 v20, 1, v0
	v_lshlrev_b32_e32 v22, 8, v18
	v_lshlrev_b32_e32 v23, 8, v21
	s_addc_u32 s1, s11, s22
	v_or_b32_e32 v96, v20, v22
	v_or_b32_e32 v184, v23, v20
	v_mov_b32_e32 v185, v97
	v_lshl_add_u64 v[0:1], s[0:1], 0, v[96:97]
	v_lshl_add_u64 v[4:5], s[0:1], 0, v[184:185]
	v_lshl_add_u64 v[8:9], s[4:5], 0, v[96:97]
	v_lshl_add_u64 v[12:13], s[4:5], 0, v[184:185]
	flat_load_dwordx4 v[0:3], v[0:1]
	s_nop 0
	flat_load_dwordx4 v[4:7], v[4:5]
	s_nop 0
	flat_load_dwordx4 v[8:11], v[8:9]
	s_nop 0
	flat_load_dwordx4 v[12:15], v[12:13]
	v_ashrrev_i32_e32 v48, 1, v64
	s_movk_i32 s3, 0xffe0
	v_bfe_u32 v197, v64, 5, 1
	v_bfi_b32 v24, s3, v48, v64
	v_mov_b64_e32 v[16:17], s[20:21]
	v_mad_i64_i32 v[16:17], s[20:21], v24, s33, v[16:17]
	v_lshlrev_b32_e32 v180, 4, v197
	v_mov_b32_e32 v181, v97
	v_lshl_add_u64 v[16:17], v[16:17], 0, v[180:181]
	flat_load_dwordx4 v[118:121], v[16:17]
	flat_load_dwordx4 v[114:117], v[16:17] offset:32
	flat_load_dwordx4 v[126:129], v[16:17] offset:64
	flat_load_dwordx4 v[122:125], v[16:17] offset:96
	flat_load_dwordx4 v[110:113], v[16:17] offset:128
	flat_load_dwordx4 v[106:109], v[16:17] offset:160
	flat_load_dwordx4 v[102:105], v[16:17] offset:192
	flat_load_dwordx4 v[98:101], v[16:17] offset:224
	v_and_b32_e32 v25, 0xfffff0, v18
	v_lshlrev_b32_e32 v26, 1, v18
	v_and_or_b32 v25, v26, 8, v25
	v_and_b32_e32 v26, 0xfffff0, v21
	v_lshlrev_b32_e32 v21, 1, v21
	v_and_b32_e32 v24, 0x70, v64
	v_bfe_u32 v67, v64, 8, 1
	v_lshl_or_b32 v24, v67, 7, v24
	v_lshrrev_b32_e32 v27, 1, v18
	v_bfe_u32 v19, v19, 5, 2
	v_and_b32_e32 v18, 3, v18
	v_lshrrev_b32_e32 v25, 1, v25
	v_and_or_b32 v21, v21, 8, v26
	v_and_or_b32 v18, v27, 4, v18
	v_and_b32_e32 v27, 48, v20
	v_bitop3_b32 v22, v20, v22, v24 bitop3:0xde
	v_bitop3_b32 v20, v20, v23, v24 bitop3:0xde
	v_or_b32_e32 v23, v25, v19
	v_lshrrev_b32_e32 v21, 1, v21
	v_lshlrev_b32_e32 v18, 6, v18
	v_add_u32_e32 v203, 0, v20
	v_lshlrev_b32_e32 v20, 9, v23
	v_or_b32_e32 v19, v21, v19
	v_and_b32_e32 v198, 31, v64
	v_lshlrev_b32_e32 v49, 4, v64
	v_or3_b32 v16, v20, v18, v27
	v_lshlrev_b32_e32 v17, 9, v19
	v_lshlrev_b32_e32 v65, 8, v198
	v_and_b32_e32 v66, 0x70, v49
	v_bfe_u32 v67, v64, 4, 1
	v_lshl_or_b32 v66, v67, 7, v66
	v_or3_b32 v17, v17, v18, v27
	v_add_u32_e32 v204, 0, v16
	v_add_u32_e32 v202, 0, v22
	s_waitcnt vmcnt(0)
	v_add_u32_e32 v205, 0, v17
	s_add_i32 s3, 0, 0x10000
	s_cmp_lg_u32 0, -1
	v_and_b32_e32 v182, 0xffffffe0, v48
	v_and_b32_e32 v68, 63, v64
	s_mov_b32 s68, s69
	s_mov_b32 s70, s69
	s_mov_b32 s71, s69
	s_mov_b32 s72, s69
	s_mov_b32 s73, s69
	s_mov_b32 s74, s69
	s_mov_b32 s75, s69
	s_mov_b32 s76, s69
	s_waitcnt vmcnt(0) lgkmcnt(0)
	ds_write_b128 v204, v[0:3]
	ds_write_b128 v205, v[4:7]
	ds_write_b128 v202, v[8:11] offset:32768
	ds_write_b128 v203, v[12:15] offset:32768
	v_bitop3_b32 v0, v180, v65, v66 bitop3:0xde
	v_add_u32_e32 v206, 0, v0
	s_waitcnt lgkmcnt(0)
	s_barrier
	ds_read_b128 v[0:3], v206 offset:32768
	ds_read_b128 v[4:7], v206 offset:40960
	s_waitcnt lgkmcnt(1)
	v_mfma_f32_32x32x16_bf16 v[16:31], v[0:3], v[118:121], 0
	v_or_b32_e32 v0, 32, v180
	v_bitop3_b32 v0, v0, v65, v66 bitop3:0xde
	v_add_u32_e32 v211, 0, v0
	v_and_b32_e32 v9, 0xc0, v49
	v_lshlrev_b32_e32 v8, 3, v68
	s_mov_b32 s77, s69
	s_mov_b32 s78, s69
	s_waitcnt lgkmcnt(0)
	v_mfma_f32_32x32x16_bf16 v[32:47], v[4:7], v[118:121], 0
	ds_read_b128 v[0:3], v211 offset:32768
	ds_read_b128 v[4:7], v211 offset:40960
	s_mov_b32 s79, s69
	s_mov_b32 s80, s69
	s_mov_b32 s81, s69
	s_mov_b32 s82, s69
	s_mov_b32 s83, s69
	s_mov_b32 s30, 4
	s_waitcnt lgkmcnt(1)
	v_mfma_f32_32x32x16_bf16 v[16:31], v[0:3], v[114:117], v[16:31]
	v_or_b32_e32 v0, 64, v180
	v_bitop3_b32 v0, v0, v65, v66 bitop3:0xde
	v_add_u32_e32 v210, 0, v0
	v_mov_b32_e32 v199, 0
	s_waitcnt lgkmcnt(0)
	v_mfma_f32_32x32x16_bf16 v[32:47], v[4:7], v[114:117], v[32:47]
	ds_read_b128 v[0:3], v210 offset:32768
	ds_read_b128 v[4:7], v210 offset:40960
	s_waitcnt lgkmcnt(1)
	v_mfma_f32_32x32x16_bf16 v[16:31], v[0:3], v[126:129], v[16:31]
	v_or_b32_e32 v0, 0x60, v180
	v_bitop3_b32 v0, v0, v65, v66 bitop3:0xde
	v_add_u32_e32 v209, 0, v0
	s_waitcnt lgkmcnt(0)
	v_mfma_f32_32x32x16_bf16 v[32:47], v[4:7], v[126:129], v[32:47]
	ds_read_b128 v[0:3], v209 offset:32768
	ds_read_b128 v[4:7], v209 offset:40960
	s_waitcnt lgkmcnt(1)
	v_mfma_f32_32x32x16_bf16 v[16:31], v[0:3], v[122:125], v[16:31]
	v_or_b32_e32 v0, 0x80, v180
	v_bitop3_b32 v0, v0, v65, v66 bitop3:0xde
	v_add_u32_e32 v208, 0, v0
	ds_read_b128 v[0:3], v208 offset:32768
	s_waitcnt lgkmcnt(1)
	v_mfma_f32_32x32x16_bf16 v[32:47], v[4:7], v[122:125], v[32:47]
	ds_read_b128 v[4:7], v208 offset:40960
	s_waitcnt lgkmcnt(1)
	v_mfma_f32_32x32x16_bf16 v[16:31], v[0:3], v[110:113], v[16:31]
	v_or_b32_e32 v1, 0xa0, v180
	v_bitop3_b32 v1, v1, v65, v66 bitop3:0xde
	v_and_b32_e32 v0, 0x3fffffc0, v64
	v_add_u32_e32 v207, 0, v1
	v_lshl_add_u32 v181, v0, 2, s3
	ds_read_b128 v[0:3], v207 offset:32768
	s_cselect_b32 s3, 0, 0
	s_add_u32 s20, s0, 0x4000
	s_addc_u32 s21, s1, 0
	s_add_u32 s24, s4, 0x4000
	s_waitcnt lgkmcnt(1)
; #define SWRITE(b, i) do { *(bf16x8*)((char*)V_lds + (b) * SHM_V + vst0) = sr_[i].vs0;          \
;     *(bf16x8*)((char*)V_lds + (b) * SHM_V + vst1) = sr_[i].vs1; int kc = sc * 2;               \
;     *(bf16x8*)((char*)K_lds + (b) * SHM_K + KSWZ(sr, kc)) = sr_[i].ks0;                       \
;     *(bf16x8*)((char*)K_lds + (b) * SHM_K + KSWZ(32 + sr, kc)) = sr_[i].ks1; } while (0)
; #define SWAIT() asm volatile("s_waitcnt vmcnt(4)" ::: "memory")
; __device__ __forceinline__ void partialSM(f32x16& p0, f32x16& p1, float& m_reg, float& mn, float& alpha) {
;   constexpr float C = SCALE * 1.4426950408889634f;
;   float pmax = p0[0];
; #pragma unroll
;   for (int r = 1; r < 16; ++r) pmax = fmaxf(pmax, p0[r]);
; #pragma unroll
;   for (int r = 0; r < 16; ++r) pmax = fmaxf(pmax, p1[r]);
;   { auto rr = __builtin_amdgcn_permlane32_swap(__float_as_uint(pmax), __float_as_uint(pmax), false, false);
;     pmax = fmaxf(__uint_as_float(rr[0]), __uint_as_float(rr[1])); }
;   if (__builtin_expect(__all(pmax - m_reg <= THR / SCALE), 1)) { mn = m_reg; alpha = 1.f; }
;   else { mn = fmaxf(m_reg, pmax); alpha = __builtin_amdgcn_exp2f((m_reg - mn) * C); m_reg = mn; }
;   float mnC = -mn * C;
; #pragma unroll
;   for (int r = 0; r < 16; ++r) p0[r] = fmaf(p0[r], C, mnC);
; #pragma unroll
;   for (int r = 0; r < 16; ++r) p1[r] = fmaf(p1[r], C, mnC);
; #pragma unroll
;   for (int r = 0; r < 16; ++r) p0[r] = __builtin_amdgcn_exp2f(p0[r]);
; }
; __device__ __forceinline__ void attn_body(const bf16_t* __restrict__ Qb, const bf16_t* __restrict__ Kh, const bf16_t* __restrict__ Vh,
;                                           bf16_t* __restrict__ Ob, const bf16_t* __restrict__ AGb, int seq, char* lds) {
;     ...
;   qkt(pA0, pA1, K_lds, qr, r32, hi); partialSM(pA0, pA1, m_reg, mnA, alA);
;   SLOAD(SO, KVBLK); if (2 < NT) SLOAD(SE, 2 * KVBLK);
;   SWAIT(); SWRITE(1, SO); __syncthreads();
	v_mfma_f32_32x32x16_bf16 v[32:47], v[4:7], v[110:113], v[32:47]
	ds_read_b128 v[4:7], v207 offset:40960
	s_addc_u32 s25, s5, 0
	s_add_u32 s4, s4, 0x8000
	s_addc_u32 s5, s5, 0
	s_add_u32 s0, s0, 0x8000
	s_addc_u32 s1, s1, 0
	v_lshl_add_u32 v183, v198, 2, v181
	s_waitcnt lgkmcnt(1)
	v_mfma_f32_32x32x16_bf16 v[16:31], v[0:3], v[106:109], v[16:31]
	v_lshl_add_u64 v[0:1], s[20:21], 0, v[96:97]
	v_lshl_add_u64 v[2:3], s[20:21], 0, v[184:185]
	flat_load_dwordx4 v[48:51], v[0:1]
	flat_load_dwordx4 v[52:55], v[2:3]
	v_lshl_add_u64 v[0:1], s[24:25], 0, v[96:97]
	v_lshl_add_u64 v[2:3], s[24:25], 0, v[184:185]
	flat_load_dwordx4 v[56:59], v[0:1]
	flat_load_dwordx4 v[60:63], v[2:3]
	v_or_b32_e32 v0, 0xc0, v180
	v_bitop3_b32 v0, v0, v65, v66 bitop3:0xde
	v_add_u32_e32 v213, 0, v0
	ds_read_b128 v[0:3], v213 offset:32768
	s_waitcnt lgkmcnt(0)
	v_mfma_f32_32x32x16_bf16 v[32:47], v[4:7], v[106:109], v[32:47]
	v_lshlrev_b32_e32 v5, 1, v64
	v_and_or_b32 v4, v8, 24, v9
	v_and_b32_e32 v5, 32, v5
	v_and_b32_e32 v6, 0x100, v8
	v_or3_b32 v69, v4, v5, v6
	ds_read_b128 v[4:7], v213 offset:40960
	v_add_u32_e32 v201, s3, v69
	v_mfma_f32_32x32x16_bf16 v[16:31], v[0:3], v[102:105], v[16:31]
	v_or_b32_e32 v0, 0xe0, v180
	v_bitop3_b32 v0, v0, v65, v66 bitop3:0xde
	v_add_u32_e32 v212, 0, v0
	ds_read_b128 v[0:3], v212 offset:32768
	ds_read_b128 v[64:67], v212 offset:40960
	s_waitcnt lgkmcnt(0)
	v_mfma_f32_32x32x16_bf16 v[32:47], v[4:7], v[102:105], v[32:47]
	v_mfma_f32_32x32x16_bf16 v[16:31], v[0:3], v[98:101], v[16:31]
	v_mov_b64_e32 v[0:1], s[68:69]
	v_mov_b64_e32 v[14:15], s[82:83]
	v_mov_b64_e32 v[2:3], s[70:71]
	v_mov_b64_e32 v[4:5], s[72:73]
	v_mov_b64_e32 v[6:7], s[74:75]
	v_mov_b64_e32 v[8:9], s[76:77]
	v_mov_b64_e32 v[10:11], s[78:79]
	v_mfma_f32_32x32x16_bf16 v[32:47], v[64:67], v[98:101], v[32:47]
	s_nop 3
	v_max_f32_e32 v64, v17, v17
	v_max_f32_e32 v65, v16, v16
	v_max_f32_e32 v64, v65, v64
	v_max3_f32 v64, v64, v18, v19
	v_max3_f32 v64, v64, v20, v21
	v_max3_f32 v64, v64, v22, v23
	v_max3_f32 v64, v64, v24, v25
	v_max3_f32 v64, v64, v26, v27
	v_max3_f32 v64, v64, v28, v29
	v_max3_f32 v64, v64, v30, v31
	v_max3_f32 v64, v64, v32, v33
	v_max3_f32 v64, v64, v34, v35
	v_max3_f32 v64, v64, v36, v37
	v_max3_f32 v70, v64, v38, v39
	v_lshl_add_u64 v[64:65], s[4:5], 0, v[184:185]
	v_lshl_add_u64 v[66:67], s[4:5], 0, v[96:97]
	flat_load_dwordx4 v[142:145], v[64:65]
	flat_load_dwordx4 v[138:141], v[66:67]
	v_lshl_add_u64 v[64:65], s[0:1], 0, v[184:185]
	v_lshl_add_u64 v[66:67], s[0:1], 0, v[96:97]
	flat_load_dwordx4 v[134:137], v[64:65]
	flat_load_dwordx4 v[130:133], v[66:67]
	v_max3_f32 v64, v70, v40, v41
	v_max3_f32 v64, v64, v42, v43
	v_max3_f32 v64, v64, v44, v45
	v_max3_f32 v64, v64, v46, v47
	v_mov_b32_e32 v65, v64
	s_nop 1
	v_permlane32_swap_b32_e32 v64, v65
	v_max_f32_e32 v65, v65, v65
	v_max_f32_e32 v64, v64, v64
	v_max_f32_e32 v64, v64, v65
	v_add_f32_e32 v65, 0x7149f2ca, v64
	v_cmp_ge_f32_e32 vcc, s62, v65
	s_cmp_eq_u64 vcc, exec
	s_waitcnt vmcnt(4)
	s_waitcnt vmcnt(0)
	ds_write_b128 v204, v[48:51] offset:16384
	ds_write_b128 v205, v[52:55] offset:16384
	ds_write_b128 v202, v[56:59] offset:49152
	ds_write_b128 v203, v[60:63] offset:49152
	v_max_f32_e32 v48, 0xf149f2ca, v64
	s_cselect_b64 vcc, -1, 0
	v_cndmask_b32_e32 v170, v48, v194, vcc
	v_sub_f32_e32 v49, 0xf149f2ca, v48
	v_mul_f32_e32 v48, 0xbe0293ee, v170
	v_fmamk_f32 v16, v16, 0x3e0293ee, v48
	v_exp_f32_e32 v163, v16
	v_fmamk_f32 v16, v17, 0x3e0293ee, v48
	v_exp_f32_e32 v177, v16
	v_fmamk_f32 v16, v18, 0x3e0293ee, v48
	v_exp_f32_e32 v164, v16
	v_fmamk_f32 v16, v19, 0x3e0293ee, v48
	v_exp_f32_e32 v186, v16
	v_fmamk_f32 v16, v20, 0x3e0293ee, v48
	v_exp_f32_e32 v176, v16
	v_fmamk_f32 v16, v21, 0x3e0293ee, v48
	v_exp_f32_e32 v187, v16
	v_fmamk_f32 v16, v22, 0x3e0293ee, v48
	v_exp_f32_e32 v165, v16
	v_fmamk_f32 v16, v23, 0x3e0293ee, v48
	v_exp_f32_e32 v175, v16
	v_fmamk_f32 v16, v24, 0x3e0293ee, v48
	v_mul_f32_e32 v49, 0x3e0293ee, v49
	v_exp_f32_e32 v166, v16
	v_fmamk_f32 v16, v25, 0x3e0293ee, v48
	v_exp_f32_e32 v49, v49
	v_exp_f32_e32 v173, v16
	v_fmamk_f32 v16, v26, 0x3e0293ee, v48
	v_exp_f32_e32 v167, v16
	v_fmamk_f32 v16, v27, 0x3e0293ee, v48
	v_exp_f32_e32 v174, v16
	v_fmamk_f32 v16, v28, 0x3e0293ee, v48
	v_exp_f32_e32 v168, v16
	v_fmamk_f32 v16, v29, 0x3e0293ee, v48
	v_pk_fma_f32 v[146:147], v[46:47], s[6:7], v[48:49] op_sel_hi:[1,0,0]
	v_pk_fma_f32 v[152:153], v[44:45], s[6:7], v[48:49] op_sel_hi:[1,0,0]
	v_pk_fma_f32 v[156:157], v[42:43], s[6:7], v[48:49] op_sel_hi:[1,0,0]
	v_pk_fma_f32 v[148:149], v[40:41], s[6:7], v[48:49] op_sel_hi:[1,0,0]
	v_pk_fma_f32 v[150:151], v[38:39], s[6:7], v[48:49] op_sel_hi:[1,0,0]
	v_pk_fma_f32 v[154:155], v[36:37], s[6:7], v[48:49] op_sel_hi:[1,0,0]
	v_pk_fma_f32 v[158:159], v[34:35], s[6:7], v[48:49] op_sel_hi:[1,0,0]
	v_pk_fma_f32 v[160:161], v[32:33], s[6:7], v[48:49] op_sel_hi:[1,0,0]
	v_exp_f32_e32 v171, v16
	v_fmamk_f32 v16, v30, 0x3e0293ee, v48
	v_fmac_f32_e32 v48, 0x3e0293ee, v31
	v_exp_f32_e32 v169, v16
	v_exp_f32_e32 v172, v48
	s_addk_i32 s3, 0x4000
	v_mov_b64_e32 v[12:13], s[80:81]
	v_cndmask_b32_e64 v214, v49, 1.0, vcc
	s_add_u32 s20, s54, s23
	v_mov_b64_e32 v[62:63], v[14:15]
	v_mov_b64_e32 v[46:47], v[14:15]
	v_mov_b64_e32 v[30:31], v[14:15]
	v_cmp_gt_u32_e64 s[4:5], 32, v68
	v_add_u32_e32 v200, s3, v69
	s_addc_u32 s21, s55, s22
	v_mov_b64_e32 v[60:61], v[12:13]
	v_mov_b64_e32 v[58:59], v[10:11]
	v_mov_b64_e32 v[56:57], v[8:9]
	v_mov_b64_e32 v[54:55], v[6:7]
	v_mov_b64_e32 v[52:53], v[4:5]
	v_mov_b64_e32 v[50:51], v[2:3]
	v_mov_b64_e32 v[48:49], v[0:1]
	v_mov_b64_e32 v[44:45], v[12:13]
	v_mov_b64_e32 v[42:43], v[10:11]
	v_mov_b64_e32 v[40:41], v[8:9]
	v_mov_b64_e32 v[38:39], v[6:7]
	v_mov_b64_e32 v[36:37], v[4:5]
	v_mov_b64_e32 v[34:35], v[2:3]
	v_mov_b64_e32 v[32:33], v[0:1]
	v_mov_b64_e32 v[28:29], v[12:13]
	v_mov_b64_e32 v[26:27], v[10:11]
	v_mov_b64_e32 v[24:25], v[8:9]
	v_mov_b64_e32 v[22:23], v[6:7]
	v_mov_b64_e32 v[20:21], v[4:5]
	v_mov_b64_e32 v[18:19], v[2:3]
	v_mov_b64_e32 v[16:17], v[0:1]
	s_waitcnt lgkmcnt(0)
	s_barrier
